# adds: next-tile prefetch in the three remaining weight-transpose loops (w_out_a, Wz, w_out_b)
# speedup vs baseline: 1.0035x; 1.0035x over previous
; DI unsigned cvt_pk_bf16(float lo, float hi) { unsigned r; asm("v_cvt_pk_bf16_f32 %0, %1, %2" : "=v"(r) : "v"(lo), "v"(hi)); return r; }
; DI void conv_tile(float* tile, bf16_t* dst, int Kdim, const float* src, int ld, int n0, int k0, int sc0, int nvalid) {
;     const int tid = threadIdx.x;
; #pragma unroll
;     for (int it = 0; it < 2; ++it) {
;         const int idx = tid + 512 * it, kk = idx >> 4, c4 = (idx & 15) * 4;
;         f32x4 v = (f32x4){0.f, 0.f, 0.f, 0.f};
;         if (c4 < nvalid) v = *(const f32x4*)(src + (size_t)(k0 + kk) * ld + sc0 + c4);
;         float* tp = tile + kk * 65 + c4; tp[0] = v[0]; tp[1] = v[1]; tp[2] = v[2]; tp[3] = v[3];
;     }
;     __syncthreads();
;     { const int n = tid >> 3, k8 = (tid & 7) * 8; const float* tp = tile + k8 * 65 + n;
;       u32x4 w; w.x = cvt_pk_bf16(tp[0], tp[65]); w.y = cvt_pk_bf16(tp[130], tp[195]); w.z = cvt_pk_bf16(tp[260], tp[325]); w.w = cvt_pk_bf16(tp[390], tp[455]);
;       *(u32x4*)(dst + (size_t)(n0 + n) * Kdim + k0 + k8) = w; }
;     __syncthreads();
; }
; __device__ void phase_prep(const Params& p, unsigned char* shm) {
;     ...
;     for (int t = b; t < 32 * 64; t += nb) { const int nblk = t >> 6, kb = t & 63; conv_tile(tile, WOUTA, 4096, p.in[7], 2048, nblk * 64, kb * 64, nblk * 64, 64); }
.LBB0_93:
	s_and_b32 s8, s3, 0xffffffc0
	s_and_b32 s6, s0, 0xfc0
	s_ashr_i32 s9, s8, 31
	v_or_b32_e32 v0, s6, v8
	v_lshl_add_u64 v[18:19], s[8:9], 2, v[4:5]
	v_lshlrev_b32_e32 v0, 11, v0
	v_lshl_add_u64 v[14:15], v[0:1], 2, v[18:19]
	v_add_lshl_u32 v0, s6, v9, 11
	global_load_dwordx4 v[30:33], v[14:15], off
	v_lshl_add_u64 v[18:19], v[0:1], 2, v[18:19]
	global_load_dwordx4 v[34:37], v[18:19], off
	v_add_u32_e32 v38, s8, v10
	v_ashrrev_i32_e32 v39, 31, v38
	v_lshlrev_b64 v[38:39], 13, v[38:39]
	s_lshl_b32 s6, s6, 1
	v_lshl_add_u64 v[38:39], s[4:5], 0, v[38:39]
	s_add_i32 s3, s3, s30
	s_add_i32 s0, s0, s1
	v_lshl_add_u64 v[38:39], v[38:39], 0, s[6:7]
	s_cmpk_lt_i32 s3, 0x800
	v_lshl_add_u64 v[38:39], v[38:39], 0, v[2:3]
	s_cselect_b64 s[98:99], -1, 0
	s_waitcnt vmcnt(0)
.Lcv_a_loop:
	s_waitcnt vmcnt(1)
	ds_write2_b32 v12, v30, v31 offset1:1
	ds_write2_b32 v12, v32, v33 offset0:2 offset1:3
	ds_write2_b32 v13, v34, v35 offset1:1
	ds_write2_b32 v13, v36, v37 offset0:2 offset1:3
	s_waitcnt lgkmcnt(0)
	s_barrier
	v_mov_b64 v[22:23], v[38:39]
	s_mov_b64 s[100:101], s[98:99]
	s_and_b64 vcc, exec, s[98:99]
	s_cbranch_vccz .Lcv_a_nonext
	s_and_b32 s8, s3, 0xffffffc0
	s_and_b32 s6, s0, 0xfc0
	s_ashr_i32 s9, s8, 31
	v_or_b32_e32 v0, s6, v8
	v_lshl_add_u64 v[18:19], s[8:9], 2, v[4:5]
	v_lshlrev_b32_e32 v0, 11, v0
	v_lshl_add_u64 v[14:15], v[0:1], 2, v[18:19]
	v_add_lshl_u32 v0, s6, v9, 11
	global_load_dwordx4 v[30:33], v[14:15], off
	v_lshl_add_u64 v[18:19], v[0:1], 2, v[18:19]
	global_load_dwordx4 v[34:37], v[18:19], off
	v_add_u32_e32 v38, s8, v10
	v_ashrrev_i32_e32 v39, 31, v38
	v_lshlrev_b64 v[38:39], 13, v[38:39]
	s_lshl_b32 s6, s6, 1
	v_lshl_add_u64 v[38:39], s[4:5], 0, v[38:39]
	s_add_i32 s3, s3, s30
	s_add_i32 s0, s0, s1
	v_lshl_add_u64 v[38:39], v[38:39], 0, s[6:7]
	s_cmpk_lt_i32 s3, 0x800
	v_lshl_add_u64 v[38:39], v[38:39], 0, v[2:3]
	s_cselect_b64 s[98:99], -1, 0
.Lcv_a_nonext:
	ds_read2_b32 v[14:15], v11 offset1:65
	ds_read2_b32 v[16:17], v11 offset0:130 offset1:195
	ds_read2_b32 v[18:19], v6 offset0:4 offset1:69
	ds_read2_b32 v[20:21], v6 offset0:134 offset1:199
	s_waitcnt lgkmcnt(3)
	v_cvt_pk_bf16_f32 v14, v14, v15
	s_waitcnt lgkmcnt(2)
	v_cvt_pk_bf16_f32 v15, v16, v17
	s_waitcnt lgkmcnt(1)
	v_cvt_pk_bf16_f32 v16, v18, v19
	s_waitcnt lgkmcnt(0)
	v_cvt_pk_bf16_f32 v17, v20, v21
	global_store_dwordx4 v[22:23], v[14:17], off
	s_barrier
	s_and_b64 vcc, exec, s[100:101]
	s_cbranch_vccnz .Lcv_a_loop

; DI unsigned cvt_pk_bf16(float lo, float hi) { unsigned r; asm("v_cvt_pk_bf16_f32 %0, %1, %2" : "=v"(r) : "v"(lo), "v"(hi)); return r; }
; DI bf16_t* wz_ptr(const Params& p) { return (bf16_t*)p.out + (size_t)T * DM; }
; DI bf16_t* woutb_ptr(const Params& p) { return wz_ptr(p) + (size_t)4096 * 2048; }
; DI void conv_tile(float* tile, bf16_t* dst, int Kdim, const float* src, int ld, int n0, int k0, int sc0, int nvalid) {
;     const int tid = threadIdx.x;
; #pragma unroll
;     for (int it = 0; it < 2; ++it) {
;         const int idx = tid + 512 * it, kk = idx >> 4, c4 = (idx & 15) * 4;
;         f32x4 v = (f32x4){0.f, 0.f, 0.f, 0.f};
;         if (c4 < nvalid) v = *(const f32x4*)(src + (size_t)(k0 + kk) * ld + sc0 + c4);
;         float* tp = tile + kk * 65 + c4; tp[0] = v[0]; tp[1] = v[1]; tp[2] = v[2]; tp[3] = v[3];
;     }
;     __syncthreads();
;     { const int n = tid >> 3, k8 = (tid & 7) * 8; const float* tp = tile + k8 * 65 + n;
;       u32x4 w; w.x = cvt_pk_bf16(tp[0], tp[65]); w.y = cvt_pk_bf16(tp[130], tp[195]); w.z = cvt_pk_bf16(tp[260], tp[325]); w.w = cvt_pk_bf16(tp[390], tp[455]);
;       *(u32x4*)(dst + (size_t)(n0 + n) * Kdim + k0 + k8) = w; }
;     __syncthreads();
; }
; __device__ void phase_convB2(const Params& p, unsigned char* shm) {
;     float* tile = (float*)shm; bf16_t* WZ = wz_ptr(p); bf16_t* WO = woutb_ptr(p);
;     for (int t = blockIdx.x; t < 64 * 32; t += gridDim.x) { const int nblk = t >> 5, kb = t & 31; conv_tile(tile, WZ, 2048, p.in[8], 10272, nblk * 64, kb * 64, 6144 + nblk * 64, 64); }
;     for (int t = blockIdx.x; t < 32 * 64; t += gridDim.x) { const int nblk = t >> 6, kb = t & 63; conv_tile(tile, WO, 4096, p.in[12], 2048, nblk * 64, kb * 64, nblk * 64, 64); }
; }
.LBB0_430:
	s_and_b32 s16, s3, 0xffffffc0
	s_ashr_i32 s17, s16, 31
	s_and_b32 s8, s13, 0x7c0
	s_lshl_b64 s[18:19], s[16:17], 2
	s_add_u32 s18, s36, s18
	s_addc_u32 s19, s37, s19
	v_or_b32_e32 v0, s8, v16
	v_lshl_add_u64 v[4:5], s[18:19], 0, v[8:9]
	v_mul_u32_u24_e32 v0, 0x2820, v0
	v_lshl_add_u64 v[12:13], v[4:5], 0, s[10:11]
	v_add_u32_e32 v3, s8, v17
	v_lshl_add_u64 v[4:5], v[0:1], 2, v[12:13]
	v_mul_u32_u24_e32 v0, 0x2820, v3
	global_load_dwordx4 v[30:33], v[4:5], off
	v_lshl_add_u64 v[12:13], v[0:1], 2, v[12:13]
	global_load_dwordx4 v[34:37], v[12:13], off
	v_add_u32_e32 v38, s16, v18
	v_ashrrev_i32_e32 v39, 31, v38
	v_lshlrev_b64 v[38:39], 12, v[38:39]
	v_lshl_add_u64 v[38:39], s[6:7], 0, v[38:39]
	s_lshl_b32 s8, s8, 1
	s_add_i32 s14, s14, s30
	s_add_i32 s13, s13, s1
	s_add_i32 s3, s3, s12
	v_lshl_add_u64 v[38:39], v[38:39], 0, s[8:9]
	s_cmpk_lt_i32 s14, 0x800
	v_lshl_add_u64 v[38:39], v[38:39], 0, v[10:11]
	s_cselect_b64 s[98:99], -1, 0
	s_waitcnt vmcnt(0)
.Lcv_b_loop:
	s_waitcnt vmcnt(1)
	ds_write2_b32 v20, v30, v31 offset1:1
	ds_write2_b32 v20, v32, v33 offset0:2 offset1:3
	ds_write2_b32 v21, v34, v35 offset1:1
	ds_write2_b32 v21, v36, v37 offset0:2 offset1:3
	s_waitcnt lgkmcnt(0)
	s_barrier
	v_mov_b64 v[22:23], v[38:39]
	s_mov_b64 s[100:101], s[98:99]
	s_and_b64 vcc, exec, s[98:99]
	s_cbranch_vccz .Lcv_b_nonext
	s_and_b32 s16, s3, 0xffffffc0
	s_ashr_i32 s17, s16, 31
	s_and_b32 s8, s13, 0x7c0
	s_lshl_b64 s[18:19], s[16:17], 2
	s_add_u32 s18, s36, s18
	s_addc_u32 s19, s37, s19
	v_or_b32_e32 v0, s8, v16
	v_lshl_add_u64 v[4:5], s[18:19], 0, v[8:9]
	v_mul_u32_u24_e32 v0, 0x2820, v0
	v_lshl_add_u64 v[12:13], v[4:5], 0, s[10:11]
	v_add_u32_e32 v3, s8, v17
	v_lshl_add_u64 v[4:5], v[0:1], 2, v[12:13]
	v_mul_u32_u24_e32 v0, 0x2820, v3
	global_load_dwordx4 v[30:33], v[4:5], off
	v_lshl_add_u64 v[12:13], v[0:1], 2, v[12:13]
	global_load_dwordx4 v[34:37], v[12:13], off
	v_add_u32_e32 v38, s16, v18
	v_ashrrev_i32_e32 v39, 31, v38
	v_lshlrev_b64 v[38:39], 12, v[38:39]
	v_lshl_add_u64 v[38:39], s[6:7], 0, v[38:39]
	s_lshl_b32 s8, s8, 1
	s_add_i32 s14, s14, s30
	s_add_i32 s13, s13, s1
	s_add_i32 s3, s3, s12
	v_lshl_add_u64 v[38:39], v[38:39], 0, s[8:9]
	s_cmpk_lt_i32 s14, 0x800
	v_lshl_add_u64 v[38:39], v[38:39], 0, v[10:11]
	s_cselect_b64 s[98:99], -1, 0
.Lcv_b_nonext:
	ds_read2_b32 v[4:5], v19 offset1:65
	ds_read2_b32 v[6:7], v19 offset0:130 offset1:195
	ds_read2_b32 v[12:13], v2 offset0:4 offset1:69
	ds_read2_b32 v[14:15], v2 offset0:134 offset1:199
	s_waitcnt lgkmcnt(3)
	v_cvt_pk_bf16_f32 v4, v4, v5
	s_waitcnt lgkmcnt(2)
	v_cvt_pk_bf16_f32 v5, v6, v7
	s_waitcnt lgkmcnt(1)
	v_cvt_pk_bf16_f32 v6, v12, v13
	s_waitcnt lgkmcnt(0)
	v_cvt_pk_bf16_f32 v7, v14, v15
	global_store_dwordx4 v[22:23], v[4:7], off
	s_barrier
	s_and_b64 vcc, exec, s[100:101]
	s_cbranch_vccnz .Lcv_b_loop
	s_add_u32 s6, s50, 0xb000000
	v_mov_b32_e32 v9, 0
	s_addc_u32 s7, s51, 0
	v_lshl_add_u64 v[0:1], s[44:45], 0, v[8:9]
	s_mov_b32 s9, 0
	v_mov_b32_e32 v11, v9
	v_add_u32_e32 v2, 0x400, v19
	s_mov_b32 s3, s2
.LBB0_432:
	s_and_b32 s10, s3, 0xffffffc0
	s_and_b32 s8, s0, 0xfc0
	s_ashr_i32 s11, s10, 31
	v_or_b32_e32 v3, s8, v16
	v_lshl_add_u64 v[12:13], s[10:11], 2, v[0:1]
	v_lshlrev_b32_e32 v8, 11, v3
	v_lshl_add_u64 v[4:5], v[8:9], 2, v[12:13]
	v_add_lshl_u32 v8, s8, v17, 11
	global_load_dwordx4 v[30:33], v[4:5], off
	v_lshl_add_u64 v[12:13], v[8:9], 2, v[12:13]
	global_load_dwordx4 v[34:37], v[12:13], off
	v_add_u32_e32 v38, s10, v18
	v_ashrrev_i32_e32 v39, 31, v38
	v_lshlrev_b64 v[38:39], 13, v[38:39]
	s_lshl_b32 s8, s8, 1
	v_lshl_add_u64 v[38:39], s[6:7], 0, v[38:39]
	s_add_i32 s3, s3, s30
	s_add_i32 s0, s0, s1
	v_lshl_add_u64 v[38:39], v[38:39], 0, s[8:9]
	s_cmpk_lt_i32 s3, 0x800
	v_lshl_add_u64 v[38:39], v[38:39], 0, v[10:11]
	s_cselect_b64 s[98:99], -1, 0
	s_waitcnt vmcnt(0)
.Lcv_c_loop:
	s_waitcnt vmcnt(1)
	ds_write2_b32 v20, v30, v31 offset1:1
	ds_write2_b32 v20, v32, v33 offset0:2 offset1:3
	ds_write2_b32 v21, v34, v35 offset1:1
	ds_write2_b32 v21, v36, v37 offset0:2 offset1:3
	s_waitcnt lgkmcnt(0)
	s_barrier
	v_mov_b64 v[22:23], v[38:39]
	s_mov_b64 s[100:101], s[98:99]
	s_and_b64 vcc, exec, s[98:99]
	s_cbranch_vccz .Lcv_c_nonext
	s_and_b32 s10, s3, 0xffffffc0
	s_and_b32 s8, s0, 0xfc0
	s_ashr_i32 s11, s10, 31
	v_or_b32_e32 v3, s8, v16
	v_lshl_add_u64 v[12:13], s[10:11], 2, v[0:1]
	v_lshlrev_b32_e32 v8, 11, v3
	v_lshl_add_u64 v[4:5], v[8:9], 2, v[12:13]
	v_add_lshl_u32 v8, s8, v17, 11
	global_load_dwordx4 v[30:33], v[4:5], off
	v_lshl_add_u64 v[12:13], v[8:9], 2, v[12:13]
	global_load_dwordx4 v[34:37], v[12:13], off
	v_add_u32_e32 v38, s10, v18
	v_ashrrev_i32_e32 v39, 31, v38
	v_lshlrev_b64 v[38:39], 13, v[38:39]
	s_lshl_b32 s8, s8, 1
	v_lshl_add_u64 v[38:39], s[6:7], 0, v[38:39]
	s_add_i32 s3, s3, s30
	s_add_i32 s0, s0, s1
	v_lshl_add_u64 v[38:39], v[38:39], 0, s[8:9]
	s_cmpk_lt_i32 s3, 0x800
	v_lshl_add_u64 v[38:39], v[38:39], 0, v[10:11]
	s_cselect_b64 s[98:99], -1, 0
.Lcv_c_nonext:
	ds_read2_b32 v[4:5], v19 offset1:65
	ds_read2_b32 v[6:7], v19 offset0:130 offset1:195
	ds_read2_b32 v[12:13], v2 offset0:4 offset1:69
	ds_read2_b32 v[14:15], v2 offset0:134 offset1:199
	s_waitcnt lgkmcnt(3)
	v_cvt_pk_bf16_f32 v4, v4, v5
	s_waitcnt lgkmcnt(2)
	v_cvt_pk_bf16_f32 v5, v6, v7
	s_waitcnt lgkmcnt(1)
	v_cvt_pk_bf16_f32 v6, v12, v13
	s_waitcnt lgkmcnt(0)
	v_cvt_pk_bf16_f32 v7, v14, v15
	global_store_dwordx4 v[22:23], v[4:7], off
	s_barrier
	s_and_b64 vcc, exec, s[100:101]
	s_cbranch_vccnz .Lcv_c_loop
